# work queue order: SGU blocks first (heaviest item), then LRU pass 2, pooling, output norm
# speedup vs baseline: 1.0374x; 1.0012x over previous
.Lq_map_done:
	s_cmpk_gt_i32 s28, 0x37f
	s_cselect_b64 s[54:55], -1, 0
	s_and_b64 vcc, exec, s[54:55]
	s_cbranch_vccnz .LBB0_572
	s_and_saveexec_b64 s[4:5], s[38:39]
	s_cbranch_execz .LBB0_579
	v_mov_b64_e32 v[0:1], s[92:93]
	s_waitcnt vmcnt(0)
	flat_atomic_add v78, v[0:1], v230 sc0
	s_or_b64 exec, exec, s[4:5]
	s_cmpk_gt_i32 s28, 0xff
	s_mov_b64 s[4:5], -1
	s_cbranch_scc1 .LBB0_580
